# out GEMM unit also drains stores before its k-loop refills fragment registers
# baseline (speedup 1.0000x reference)
.LBB0_1374:
	s_add_u32 s14, s14, 0x80080
	s_addc_u32 s15, s15, 0
	s_add_u32 s11, s16, 0x100
	v_mov_b32_e32 v0, 0
	s_addc_u32 s13, s17, 0
	s_mov_b32 s39, -2
	v_mov_b32_e32 v1, v0
	v_mov_b32_e32 v2, v0
	v_mov_b32_e32 v3, v0
	v_mov_b32_e32 v4, v0
	v_mov_b32_e32 v5, v0
	v_mov_b32_e32 v6, v0
	v_mov_b32_e32 v7, v0
	v_mov_b32_e32 v8, v0
	v_mov_b32_e32 v9, v0
	v_mov_b32_e32 v10, v0
	v_mov_b32_e32 v11, v0
	v_mov_b32_e32 v16, v0
	v_mov_b32_e32 v17, v0
	v_mov_b32_e32 v18, v0
	v_mov_b32_e32 v19, v0
	v_mov_b32_e32 v24, v0
	v_mov_b32_e32 v25, v0
	v_mov_b32_e32 v26, v0
	v_mov_b32_e32 v27, v0
	v_mov_b32_e32 v34, v0
	v_mov_b32_e32 v35, v0
	v_mov_b32_e32 v36, v0
	v_mov_b32_e32 v37, v0
	v_mov_b32_e32 v42, v0
	v_mov_b32_e32 v43, v0
	v_mov_b32_e32 v44, v0
	v_mov_b32_e32 v45, v0
	v_mov_b32_e32 v46, v0
	v_mov_b32_e32 v47, v0
	v_mov_b32_e32 v48, v0
	v_mov_b32_e32 v49, v0
	v_mov_b32_e32 v12, v0
	v_mov_b32_e32 v13, v0
	v_mov_b32_e32 v14, v0
	v_mov_b32_e32 v15, v0
	v_mov_b32_e32 v20, v0
	v_mov_b32_e32 v21, v0
	v_mov_b32_e32 v22, v0
	v_mov_b32_e32 v23, v0
	v_mov_b32_e32 v28, v0
	v_mov_b32_e32 v29, v0
	v_mov_b32_e32 v30, v0
	v_mov_b32_e32 v31, v0
	v_mov_b32_e32 v38, v0
	v_mov_b32_e32 v39, v0
	v_mov_b32_e32 v40, v0
	v_mov_b32_e32 v41, v0
	v_mov_b32_e32 v50, v0
	v_mov_b32_e32 v51, v0
	v_mov_b32_e32 v52, v0
	v_mov_b32_e32 v53, v0
	v_mov_b32_e32 v54, v0
	v_mov_b32_e32 v55, v0
	v_mov_b32_e32 v56, v0
	v_mov_b32_e32 v57, v0
	v_mov_b32_e32 v58, v0
	v_mov_b32_e32 v59, v0
	v_mov_b32_e32 v60, v0
	v_mov_b32_e32 v61, v0
	v_mov_b32_e32 v62, v0
	v_mov_b32_e32 v63, v0
	v_mov_b32_e32 v64, v0
	v_mov_b32_e32 v65, v0
	v_mov_b32_e32 v66, v0
	v_mov_b32_e32 v67, v0
	v_mov_b32_e32 v68, v0
	v_mov_b32_e32 v69, v0
	v_mov_b32_e32 v70, v0
	v_mov_b32_e32 v71, v0
	v_mov_b32_e32 v72, v0
	v_mov_b32_e32 v73, v0
	v_mov_b32_e32 v74, v0
	v_mov_b32_e32 v75, v0
	v_mov_b32_e32 v76, v0
	v_mov_b32_e32 v77, v0
	v_mov_b32_e32 v82, v0
	v_mov_b32_e32 v83, v0
	v_mov_b32_e32 v84, v0
	v_mov_b32_e32 v85, v0
	v_mov_b32_e32 v90, v0
	v_mov_b32_e32 v91, v0
	v_mov_b32_e32 v92, v0
	v_mov_b32_e32 v93, v0
	v_mov_b32_e32 v98, v0
	v_mov_b32_e32 v99, v0
	v_mov_b32_e32 v100, v0
	v_mov_b32_e32 v101, v0
	v_mov_b32_e32 v102, v0
	v_mov_b32_e32 v103, v0
	v_mov_b32_e32 v104, v0
	v_mov_b32_e32 v105, v0
	v_mov_b32_e32 v106, v0
	v_mov_b32_e32 v107, v0
	v_mov_b32_e32 v108, v0
	v_mov_b32_e32 v109, v0
	v_mov_b32_e32 v78, v0
	v_mov_b32_e32 v79, v0
	v_mov_b32_e32 v80, v0
	v_mov_b32_e32 v81, v0
	v_mov_b32_e32 v86, v0
	v_mov_b32_e32 v87, v0
	v_mov_b32_e32 v88, v0
	v_mov_b32_e32 v89, v0
	v_mov_b32_e32 v94, v0
	v_mov_b32_e32 v95, v0
	v_mov_b32_e32 v96, v0
	v_mov_b32_e32 v97, v0
	v_mov_b32_e32 v110, v0
	v_mov_b32_e32 v111, v0
	v_mov_b32_e32 v112, v0
	v_mov_b32_e32 v113, v0
	v_mov_b32_e32 v114, v0
	v_mov_b32_e32 v115, v0
	v_mov_b32_e32 v116, v0
	v_mov_b32_e32 v117, v0
	v_mov_b32_e32 v118, v0
	v_mov_b32_e32 v119, v0
	v_mov_b32_e32 v120, v0
	v_mov_b32_e32 v121, v0
	v_mov_b32_e32 v122, v0
	v_mov_b32_e32 v123, v0
	v_mov_b32_e32 v124, v0
	v_mov_b32_e32 v125, v0
	v_mov_b32_e32 v126, v0
	v_mov_b32_e32 v127, v0
	v_mov_b32_e32 v128, v0
	v_mov_b32_e32 v129, v0
	s_waitcnt vmcnt(0)
